# v13 + P0 weight-transpose loops: both 16-load batches issued before any LDS write (32 loads in flight per wave)
# baseline (speedup 1.0000x reference)
; DI void p0_transpose_item(const float* W, int K, int N, bf16_t* WT, int up_map, LAS float* scr, int item, int lane) {
;     ...
; #pragma unroll 8
;     for (int i = 0; i < 32; ++i) { const int kk = 2 * i + (lane >> 5); scr[kk * 33 + (lane & 31)] = W[(size_t)(k0 + kk) * N + n0 + (lane & 31)]; }
.LBB0_802:
	s_lshl_b32 s44, s35, 1
	s_lshl_b32 s45, s40, 1
	v_or_b32_e32 v104, s45, v14
	s_add_i32 s46, s44, 4
	s_add_i32 s47, s45, 4
	s_add_i32 s48, s44, 8
	s_add_i32 s50, s45, 8
	s_add_i32 s54, s44, 12
	s_add_i32 s55, s45, 12
	s_add_i32 s56, s44, 16
	s_add_i32 s57, s45, 16
	s_add_i32 s58, s44, 20
	s_add_i32 s59, s45, 20
	s_add_i32 s60, s44, 24
	s_add_i32 s61, s45, 24
	s_add_i32 s62, s44, 28
	s_add_i32 s63, s45, 28
	v_or_b32_e32 v102, s44, v3
	v_ashrrev_i32_e32 v105, 31, v104
	v_or_b32_e32 v106, s46, v3
	v_or_b32_e32 v108, s47, v14
	v_or_b32_e32 v110, s48, v3
	v_or_b32_e32 v112, s50, v14
	v_or_b32_e32 v114, s54, v3
	v_or_b32_e32 v116, s55, v14
	v_or_b32_e32 v118, s56, v3
	v_or_b32_e32 v120, s57, v14
	v_or_b32_e32 v122, s58, v3
	v_or_b32_e32 v124, s59, v14
	v_or_b32_e32 v126, s60, v3
	v_or_b32_e32 v156, s61, v14
	v_or_b32_e32 v158, s62, v3
	v_or_b32_e32 v160, s63, v14
	v_ashrrev_i32_e32 v103, 31, v102
	v_lshlrev_b64 v[104:105], 13, v[104:105]
	v_ashrrev_i32_e32 v109, 31, v108
	v_ashrrev_i32_e32 v107, 31, v106
	v_ashrrev_i32_e32 v113, 31, v112
	v_ashrrev_i32_e32 v111, 31, v110
	v_ashrrev_i32_e32 v117, 31, v116
	v_ashrrev_i32_e32 v115, 31, v114
	v_ashrrev_i32_e32 v121, 31, v120
	v_ashrrev_i32_e32 v119, 31, v118
	v_ashrrev_i32_e32 v125, 31, v124
	v_ashrrev_i32_e32 v123, 31, v122
	v_ashrrev_i32_e32 v157, 31, v156
	v_ashrrev_i32_e32 v127, 31, v126
	v_ashrrev_i32_e32 v161, 31, v160
	v_ashrrev_i32_e32 v159, 31, v158
	v_lshlrev_b64 v[102:103], 13, v[102:103]
	v_lshl_add_u64 v[104:105], v[12:13], 0, v[104:105]
	v_lshlrev_b64 v[106:107], 13, v[106:107]
	v_lshlrev_b64 v[108:109], 13, v[108:109]
	v_lshlrev_b64 v[110:111], 13, v[110:111]
	v_lshlrev_b64 v[112:113], 13, v[112:113]
	v_lshlrev_b64 v[114:115], 13, v[114:115]
	v_lshlrev_b64 v[116:117], 13, v[116:117]
	v_lshlrev_b64 v[118:119], 13, v[118:119]
	v_lshlrev_b64 v[120:121], 13, v[120:121]
	v_lshlrev_b64 v[122:123], 13, v[122:123]
	v_lshlrev_b64 v[124:125], 13, v[124:125]
	v_lshlrev_b64 v[126:127], 13, v[126:127]
	v_lshlrev_b64 v[156:157], 13, v[156:157]
	v_lshlrev_b64 v[158:159], 13, v[158:159]
	v_lshlrev_b64 v[160:161], 13, v[160:161]
	v_lshl_add_u64 v[102:103], v[12:13], 0, v[102:103]
	v_lshl_add_u64 v[108:109], v[12:13], 0, v[108:109]
	v_lshl_add_u64 v[106:107], v[12:13], 0, v[106:107]
	v_lshl_add_u64 v[112:113], v[12:13], 0, v[112:113]
	v_lshl_add_u64 v[110:111], v[12:13], 0, v[110:111]
	v_lshl_add_u64 v[116:117], v[12:13], 0, v[116:117]
	v_lshl_add_u64 v[114:115], v[12:13], 0, v[114:115]
	v_lshl_add_u64 v[120:121], v[12:13], 0, v[120:121]
	v_lshl_add_u64 v[118:119], v[12:13], 0, v[118:119]
	v_lshl_add_u64 v[124:125], v[12:13], 0, v[124:125]
	v_lshl_add_u64 v[122:123], v[12:13], 0, v[122:123]
	v_lshl_add_u64 v[156:157], v[12:13], 0, v[156:157]
	v_lshl_add_u64 v[126:127], v[12:13], 0, v[126:127]
	v_lshl_add_u64 v[160:161], v[12:13], 0, v[160:161]
	v_lshl_add_u64 v[158:159], v[12:13], 0, v[158:159]
	global_load_dword v95, v[104:105], off
	global_load_dword v97, v[102:103], off
	global_load_dword v98, v[108:109], off
	global_load_dword v101, v[106:107], off
	global_load_dword v162, v[112:113], off
	global_load_dword v163, v[110:111], off
	global_load_dword v164, v[116:117], off
	global_load_dword v165, v[114:115], off
	global_load_dword v166, v[120:121], off
	global_load_dword v167, v[118:119], off
	global_load_dword v168, v[124:125], off
	global_load_dword v169, v[122:123], off
	global_load_dword v170, v[156:157], off
	global_load_dword v171, v[126:127], off
	global_load_dword v172, v[160:161], off
	global_load_dword v173, v[158:159], off
	v_or_b32_e32 v104, s44, v1
	v_or_b32_e32 v102, s45, v0
	s_add_i32 s40, s40, 16
	s_add_i32 s35, s35, 16
	s_add_i32 s41, s41, -16
	v_mad_u64_u32 v[102:103], s[44:45], v102, s53, v[4:5]
	v_mad_u64_u32 v[104:105], s[44:45], v104, s53, v[4:5]
	v_or_b32_e32 v103, s46, v1
	v_or_b32_e32 v105, s47, v0
	v_or_b32_e32 v112, s48, v1
	v_or_b32_e32 v110, s50, v0
	v_or_b32_e32 v116, s54, v1
	v_or_b32_e32 v114, s55, v0
	v_or_b32_e32 v120, s56, v1
	v_or_b32_e32 v118, s57, v0
	v_or_b32_e32 v124, s58, v1
	v_or_b32_e32 v122, s59, v0
	v_or_b32_e32 v156, s60, v1
	v_or_b32_e32 v126, s61, v0
	v_or_b32_e32 v160, s62, v1
	v_or_b32_e32 v158, s63, v0
	s_cmp_lg_u32 s41, 0
	v_mad_u64_u32 v[106:107], s[44:45], v105, s53, v[4:5]
	v_mad_u64_u32 v[108:109], s[44:45], v103, s53, v[4:5]
	v_mad_u64_u32 v[110:111], s[44:45], v110, s53, v[4:5]
	v_mad_u64_u32 v[112:113], s[44:45], v112, s53, v[4:5]
	v_mad_u64_u32 v[114:115], s[44:45], v114, s53, v[4:5]
	v_mad_u64_u32 v[116:117], s[44:45], v116, s53, v[4:5]
	v_mad_u64_u32 v[118:119], s[44:45], v118, s53, v[4:5]
	v_mad_u64_u32 v[120:121], s[44:45], v120, s53, v[4:5]
	v_mad_u64_u32 v[122:123], s[44:45], v122, s53, v[4:5]
	v_mad_u64_u32 v[124:125], s[44:45], v124, s53, v[4:5]
	v_mad_u64_u32 v[126:127], s[44:45], v126, s53, v[4:5]
	v_mad_u64_u32 v[156:157], s[44:45], v156, s53, v[4:5]
	v_mad_u64_u32 v[158:159], s[44:45], v158, s53, v[4:5]
	v_mad_u64_u32 v[160:161], s[44:45], v160, s53, v[4:5]
	s_nop 3
	s_lshl_b32 s44, s35, 1
	s_lshl_b32 s45, s40, 1
	v_or_b32_e32 v24, s45, v14
	s_add_i32 s46, s44, 4
	s_add_i32 s47, s45, 4
	s_add_i32 s48, s44, 8
	s_add_i32 s50, s45, 8
	s_add_i32 s54, s44, 12
	s_add_i32 s55, s45, 12
	s_add_i32 s56, s44, 16
	s_add_i32 s57, s45, 16
	s_add_i32 s58, s44, 20
	s_add_i32 s59, s45, 20
	s_add_i32 s60, s44, 24
	s_add_i32 s61, s45, 24
	s_add_i32 s62, s44, 28
	s_add_i32 s63, s45, 28
	v_or_b32_e32 v22, s44, v3
	v_ashrrev_i32_e32 v25, 31, v24
	v_or_b32_e32 v26, s46, v3
	v_or_b32_e32 v28, s47, v14
	v_or_b32_e32 v30, s48, v3
	v_or_b32_e32 v32, s50, v14
	v_or_b32_e32 v34, s54, v3
	v_or_b32_e32 v36, s55, v14
	v_or_b32_e32 v38, s56, v3
; DI void p0_transpose_item(const float* W, int K, int N, bf16_t* WT, int up_map, LAS float* scr, int item, int lane) {
;     ...
;     for (int i = 0; i < 32; ++i) { const int kk = 2 * i + (lane >> 5); scr[kk * 33 + (lane & 31)] = W[(size_t)(k0 + kk) * N + n0 + (lane & 31)]; }
	v_or_b32_e32 v40, s57, v14
	v_or_b32_e32 v42, s58, v3
	v_or_b32_e32 v44, s59, v14
	v_or_b32_e32 v46, s60, v3
	v_or_b32_e32 v48, s61, v14
	v_or_b32_e32 v50, s62, v3
	v_or_b32_e32 v52, s63, v14
	v_ashrrev_i32_e32 v23, 31, v22
	v_lshlrev_b64 v[24:25], 13, v[24:25]
	v_ashrrev_i32_e32 v29, 31, v28
	v_ashrrev_i32_e32 v27, 31, v26
	v_ashrrev_i32_e32 v33, 31, v32
	v_ashrrev_i32_e32 v31, 31, v30
	v_ashrrev_i32_e32 v37, 31, v36
	v_ashrrev_i32_e32 v35, 31, v34
	v_ashrrev_i32_e32 v41, 31, v40
	v_ashrrev_i32_e32 v39, 31, v38
	v_ashrrev_i32_e32 v45, 31, v44
	v_ashrrev_i32_e32 v43, 31, v42
	v_ashrrev_i32_e32 v49, 31, v48
	v_ashrrev_i32_e32 v47, 31, v46
	v_ashrrev_i32_e32 v53, 31, v52
	v_ashrrev_i32_e32 v51, 31, v50
	v_lshlrev_b64 v[22:23], 13, v[22:23]
	v_lshl_add_u64 v[24:25], v[12:13], 0, v[24:25]
	v_lshlrev_b64 v[26:27], 13, v[26:27]
	v_lshlrev_b64 v[28:29], 13, v[28:29]
	v_lshlrev_b64 v[30:31], 13, v[30:31]
	v_lshlrev_b64 v[32:33], 13, v[32:33]
	v_lshlrev_b64 v[34:35], 13, v[34:35]
	v_lshlrev_b64 v[36:37], 13, v[36:37]
	v_lshlrev_b64 v[38:39], 13, v[38:39]
	v_lshlrev_b64 v[40:41], 13, v[40:41]
	v_lshlrev_b64 v[42:43], 13, v[42:43]
	v_lshlrev_b64 v[44:45], 13, v[44:45]
	v_lshlrev_b64 v[46:47], 13, v[46:47]
	v_lshlrev_b64 v[48:49], 13, v[48:49]
	v_lshlrev_b64 v[50:51], 13, v[50:51]
	v_lshlrev_b64 v[52:53], 13, v[52:53]
	v_lshl_add_u64 v[22:23], v[12:13], 0, v[22:23]
	v_lshl_add_u64 v[28:29], v[12:13], 0, v[28:29]
	v_lshl_add_u64 v[26:27], v[12:13], 0, v[26:27]
	v_lshl_add_u64 v[32:33], v[12:13], 0, v[32:33]
	v_lshl_add_u64 v[30:31], v[12:13], 0, v[30:31]
	v_lshl_add_u64 v[36:37], v[12:13], 0, v[36:37]
	v_lshl_add_u64 v[34:35], v[12:13], 0, v[34:35]
	v_lshl_add_u64 v[40:41], v[12:13], 0, v[40:41]
	v_lshl_add_u64 v[38:39], v[12:13], 0, v[38:39]
	v_lshl_add_u64 v[44:45], v[12:13], 0, v[44:45]
	v_lshl_add_u64 v[42:43], v[12:13], 0, v[42:43]
	v_lshl_add_u64 v[48:49], v[12:13], 0, v[48:49]
	v_lshl_add_u64 v[46:47], v[12:13], 0, v[46:47]
	v_lshl_add_u64 v[52:53], v[12:13], 0, v[52:53]
	v_lshl_add_u64 v[50:51], v[12:13], 0, v[50:51]
	global_load_dword v11, v[24:25], off
	global_load_dword v15, v[22:23], off
	global_load_dword v16, v[28:29], off
	global_load_dword v21, v[26:27], off
	global_load_dword v54, v[32:33], off
	global_load_dword v55, v[30:31], off
	global_load_dword v56, v[36:37], off
	global_load_dword v57, v[34:35], off
	global_load_dword v58, v[40:41], off
	global_load_dword v59, v[38:39], off
	global_load_dword v60, v[44:45], off
	global_load_dword v61, v[42:43], off
	global_load_dword v62, v[48:49], off
	global_load_dword v63, v[46:47], off
	global_load_dword v64, v[52:53], off
	global_load_dword v65, v[50:51], off
	v_or_b32_e32 v24, s44, v1
	v_or_b32_e32 v22, s45, v0
	s_add_i32 s40, s40, 16
	s_add_i32 s35, s35, 16
	s_add_i32 s41, s41, -16
	v_mad_u64_u32 v[22:23], s[44:45], v22, s53, v[4:5]
	v_mad_u64_u32 v[24:25], s[44:45], v24, s53, v[4:5]
	v_or_b32_e32 v23, s46, v1
	v_or_b32_e32 v25, s47, v0
	v_or_b32_e32 v32, s48, v1
	v_or_b32_e32 v30, s50, v0
	v_or_b32_e32 v36, s54, v1
	v_or_b32_e32 v34, s55, v0
	v_or_b32_e32 v40, s56, v1
	v_or_b32_e32 v38, s57, v0
	v_or_b32_e32 v44, s58, v1
	v_or_b32_e32 v42, s59, v0
	v_or_b32_e32 v48, s60, v1
	v_or_b32_e32 v46, s61, v0
	v_or_b32_e32 v52, s62, v1
	v_or_b32_e32 v50, s63, v0
	s_cmp_lg_u32 s41, 0
	v_mad_u64_u32 v[26:27], s[44:45], v25, s53, v[4:5]
	v_mad_u64_u32 v[28:29], s[44:45], v23, s53, v[4:5]
	v_mad_u64_u32 v[30:31], s[44:45], v30, s53, v[4:5]
	v_mad_u64_u32 v[32:33], s[44:45], v32, s53, v[4:5]
	v_mad_u64_u32 v[34:35], s[44:45], v34, s53, v[4:5]
	v_mad_u64_u32 v[36:37], s[44:45], v36, s53, v[4:5]
	v_mad_u64_u32 v[38:39], s[44:45], v38, s53, v[4:5]
	v_mad_u64_u32 v[40:41], s[44:45], v40, s53, v[4:5]
	v_mad_u64_u32 v[42:43], s[44:45], v42, s53, v[4:5]
	v_mad_u64_u32 v[44:45], s[44:45], v44, s53, v[4:5]
	v_mad_u64_u32 v[46:47], s[44:45], v46, s53, v[4:5]
	v_mad_u64_u32 v[48:49], s[44:45], v48, s53, v[4:5]
	v_mad_u64_u32 v[50:51], s[44:45], v50, s53, v[4:5]
	v_mad_u64_u32 v[52:53], s[44:45], v52, s53, v[4:5]
	s_waitcnt vmcnt(31)
; #define LAS __attribute__((address_space(3)))
; DI unsigned pk2(float lo, float hi) { f32x2 v = {lo, hi}; return __builtin_bit_cast(unsigned, __builtin_convertvector(v, bf16x2v)); }
; #define LDS_WAIT() asm volatile("s_waitcnt lgkmcnt(0)" ::: "memory")
; DI void p0_transpose_item(const float* W, int K, int N, bf16_t* WT, int up_map, LAS float* scr, int item, int lane) {
;     ...
;     for (int i = 0; i < 32; ++i) { const int kk = 2 * i + (lane >> 5); scr[kk * 33 + (lane & 31)] = W[(size_t)(k0 + kk) * N + n0 + (lane & 31)]; }
;     LDS_WAIT(); asm volatile("" ::: "memory");
;     const int c = lane & 7;
; #pragma unroll
;     for (int j = 0; j < 4; ++j) { const int n = (lane >> 3) + 8 * j; const LAS float* s = scr + (8 * c) * 33 + n;
;         u32x4 o; o.x = pk2(s[0 * 33], s[1 * 33]); o.y = pk2(s[2 * 33], s[3 * 33]); o.z = pk2(s[4 * 33], s[5 * 33]); o.w = pk2(s[6 * 33], s[7 * 33]);
;         *(u32x4*)(WT + (size_t)(rowbase + n) * K + k0 + 8 * c) = o; }
;     LDS_WAIT(); asm volatile("" ::: "memory");
	ds_write_b32 v102, v95
	s_waitcnt vmcnt(30)
	ds_write_b32 v104, v97
	s_waitcnt vmcnt(29)
	ds_write_b32 v106, v98
	s_waitcnt vmcnt(28)
	ds_write_b32 v108, v101
	s_waitcnt vmcnt(27)
	ds_write_b32 v110, v162
	s_waitcnt vmcnt(26)
	ds_write_b32 v112, v163
	s_waitcnt vmcnt(25)
	ds_write_b32 v114, v164
	s_waitcnt vmcnt(24)
	ds_write_b32 v116, v165
	s_waitcnt vmcnt(23)
	ds_write_b32 v118, v166
	s_waitcnt vmcnt(22)
	ds_write_b32 v120, v167
	s_waitcnt vmcnt(21)
	ds_write_b32 v122, v168
	s_waitcnt vmcnt(20)
	ds_write_b32 v124, v169
	s_waitcnt vmcnt(19)
	ds_write_b32 v126, v170
	s_waitcnt vmcnt(18)
	ds_write_b32 v156, v171
	s_waitcnt vmcnt(17)
	ds_write_b32 v158, v172
	s_waitcnt vmcnt(16)
	ds_write_b32 v160, v173
	s_waitcnt vmcnt(15)
	ds_write_b32 v22, v11
	s_waitcnt vmcnt(14)
	ds_write_b32 v24, v15
	s_waitcnt vmcnt(13)
	ds_write_b32 v26, v16
	s_waitcnt vmcnt(12)
	ds_write_b32 v28, v21
	s_waitcnt vmcnt(11)
	ds_write_b32 v30, v54
	s_waitcnt vmcnt(10)
	ds_write_b32 v32, v55
	s_waitcnt vmcnt(9)
	ds_write_b32 v34, v56
	s_waitcnt vmcnt(8)
	ds_write_b32 v36, v57
	s_waitcnt vmcnt(7)
	ds_write_b32 v38, v58
	s_waitcnt vmcnt(6)
	ds_write_b32 v40, v59
	s_waitcnt vmcnt(5)
	ds_write_b32 v42, v60
	s_waitcnt vmcnt(4)
	ds_write_b32 v44, v61
	s_waitcnt vmcnt(3)
	ds_write_b32 v46, v62
	s_waitcnt vmcnt(2)
	ds_write_b32 v48, v63
	s_waitcnt vmcnt(1)
	ds_write_b32 v50, v64
	s_waitcnt vmcnt(0)
	ds_write_b32 v52, v65
	s_waitcnt lgkmcnt(0)
	ds_read2_b32 v[14:15], v17 offset0:33 offset1:41
	ds_read2_b32 v[22:23], v17 offset1:8
	ds_read2_b32 v[24:25], v17 offset0:66 offset1:74
	ds_read2_b32 v[26:27], v17 offset0:99 offset1:107
	ds_read2_b32 v[28:29], v17 offset0:132 offset1:140
	ds_read2_b32 v[30:31], v17 offset0:165 offset1:173
	ds_read2_b32 v[32:33], v17 offset0:198 offset1:206
	ds_read2_b32 v[34:35], v17 offset0:231 offset1:239
	v_mov_b64_e32 v[12:13], s[6:7]
	s_mov_b32 s35, 0x1600000
	v_mad_i64_i32 v[12:13], s[40:41], v8, s35, v[12:13]
	v_mov_b32_e32 v11, v185
	v_or_b32_e32 v3, v9, v7
	v_lshl_add_u64 v[10:11], v[10:11], 1, v[12:13]
	v_lshlrev_b32_e32 v184, 1, v6
	v_mul_u32_u24_e32 v3, 0x1600, v3
	v_lshl_add_u64 v[36:37], v[10:11], 0, v[184:185]
	v_lshlrev_b32_e32 v184, 1, v3
	s_waitcnt lgkmcnt(6)
	v_cvt_pk_bf16_f32 v10, v22, v14
	s_waitcnt lgkmcnt(4)
	v_cvt_pk_bf16_f32 v11, v24, v26
	s_waitcnt lgkmcnt(2)
	v_cvt_pk_bf16_f32 v12, v28, v30
	s_waitcnt lgkmcnt(0)
	v_cvt_pk_bf16_f32 v13, v32, v34
	v_lshl_add_u64 v[38:39], v[36:37], 0, v[184:185]
	global_store_dwordx4 v[38:39], v[10:13], off
	v_or_b32_e32 v3, v9, v18
	v_mul_u32_u24_e32 v3, 0x1600, v3
	v_cvt_pk_bf16_f32 v10, v23, v15
	v_cvt_pk_bf16_f32 v11, v25, v27
	v_cvt_pk_bf16_f32 v12, v29, v31
	v_cvt_pk_bf16_f32 v13, v33, v35
	ds_read2_b32 v[22:23], v17 offset0:16 offset1:24
	ds_read2_b32 v[24:25], v17 offset0:49 offset1:57
	ds_read2_b32 v[26:27], v17 offset0:82 offset1:90
	ds_read2_b32 v[28:29], v17 offset0:115 offset1:123
	ds_read2_b32 v[30:31], v17 offset0:148 offset1:156
	ds_read2_b32 v[32:33], v17 offset0:181 offset1:189
	ds_read2_b32 v[34:35], v17 offset0:214 offset1:222
	ds_read2_b32 v[38:39], v17 offset0:247 offset1:255
	v_lshlrev_b32_e32 v184, 1, v3
	v_or_b32_e32 v3, v9, v19
	v_mul_u32_u24_e32 v3, 0x1600, v3
	v_lshl_add_u64 v[14:15], v[36:37], 0, v[184:185]
	v_lshlrev_b32_e32 v184, 1, v3
	v_or_b32_e32 v3, v9, v20
	v_mul_u32_u24_e32 v3, 0x1600, v3
	global_store_dwordx4 v[14:15], v[10:13], off
	v_lshl_add_u64 v[14:15], v[36:37], 0, v[184:185]
	v_lshlrev_b32_e32 v184, 1, v3
	s_waitcnt lgkmcnt(6)
	v_cvt_pk_bf16_f32 v10, v22, v24
	s_waitcnt lgkmcnt(4)
	v_cvt_pk_bf16_f32 v11, v26, v28
	s_waitcnt lgkmcnt(2)
	v_cvt_pk_bf16_f32 v12, v30, v32
	s_waitcnt lgkmcnt(0)
	v_cvt_pk_bf16_f32 v13, v34, v38
	global_store_dwordx4 v[14:15], v[10:13], off
	v_lshl_add_u64 v[8:9], v[36:37], 0, v[184:185]
	v_readlane_b32 s62, v254, 14
	v_cvt_pk_bf16_f32 v10, v23, v25
	v_cvt_pk_bf16_f32 v11, v27, v29
	v_cvt_pk_bf16_f32 v12, v31, v33
	v_cvt_pk_bf16_f32 v13, v35, v39
	global_store_dwordx4 v[8:9], v[10:13], off
	s_waitcnt lgkmcnt(0)
	s_movk_i32 s63, 0x7fff

; DI void p0_transpose_item(const float* W, int K, int N, bf16_t* WT, int up_map, LAS float* scr, int item, int lane) {
;     ...
; #pragma unroll 8
;     for (int i = 0; i < 32; ++i) { const int kk = 2 * i + (lane >> 5); scr[kk * 33 + (lane & 31)] = W[(size_t)(k0 + kk) * N + n0 + (lane & 31)]; }
.LBB0_810:
	s_lshl_b32 s46, s35, 1
	s_lshl_b32 s47, s40, 1
	v_or_b32_e32 v96, s46, v3
	v_or_b32_e32 v94, s47, v12
	s_add_i32 s48, s46, 4
	s_add_i32 s50, s47, 4
	s_add_i32 s54, s46, 8
	s_add_i32 s55, s47, 8
	s_add_i32 s56, s46, 12
	s_add_i32 s57, s47, 12
	s_add_i32 s58, s46, 16
	s_add_i32 s59, s47, 16
	s_add_i32 s60, s46, 20
	s_add_i32 s61, s47, 20
	s_add_i32 s62, s46, 24
	s_add_i32 s63, s47, 24
	s_add_i32 s66, s46, 28
	s_add_i32 s67, s47, 28
	v_mad_u64_u32 v[94:95], s[44:45], v94, s51, v[10:11]
	v_mad_u64_u32 v[100:101], s[44:45], v96, s51, v[10:11]
	v_or_b32_e32 v96, s48, v3
	v_or_b32_e32 v99, s50, v12
	v_or_b32_e32 v108, s54, v3
	v_or_b32_e32 v106, s55, v12
	v_or_b32_e32 v112, s56, v3
	v_or_b32_e32 v110, s57, v12
	v_or_b32_e32 v116, s58, v3
	v_or_b32_e32 v114, s59, v12
	v_or_b32_e32 v120, s60, v3
	v_or_b32_e32 v118, s61, v12
	v_or_b32_e32 v124, s62, v3
	v_or_b32_e32 v122, s63, v12
	v_or_b32_e32 v156, s66, v3
	v_or_b32_e32 v126, s67, v12
	v_mad_u64_u32 v[102:103], s[44:45], v99, s51, v[10:11]
	v_mad_u64_u32 v[104:105], s[44:45], v96, s51, v[10:11]
	v_mad_u64_u32 v[106:107], s[44:45], v106, s51, v[10:11]
	v_mad_u64_u32 v[108:109], s[44:45], v108, s51, v[10:11]
	v_mad_u64_u32 v[110:111], s[44:45], v110, s51, v[10:11]
	v_mad_u64_u32 v[112:113], s[44:45], v112, s51, v[10:11]
	v_mad_u64_u32 v[114:115], s[44:45], v114, s51, v[10:11]
	v_mad_u64_u32 v[116:117], s[44:45], v116, s51, v[10:11]
	v_mad_u64_u32 v[118:119], s[44:45], v118, s51, v[10:11]
	v_mad_u64_u32 v[120:121], s[44:45], v120, s51, v[10:11]
	v_mad_u64_u32 v[122:123], s[44:45], v122, s51, v[10:11]
	v_mad_u64_u32 v[124:125], s[44:45], v124, s51, v[10:11]
	v_mad_u64_u32 v[126:127], s[44:45], v126, s51, v[10:11]
	v_mad_u64_u32 v[156:157], s[44:45], v156, s51, v[10:11]
	global_load_dword v96, v[94:95], off
	global_load_dword v99, v[100:101], off
	global_load_dword v158, v[102:103], off
	global_load_dword v159, v[104:105], off
	global_load_dword v160, v[106:107], off
	global_load_dword v161, v[108:109], off
	global_load_dword v162, v[110:111], off
	global_load_dword v163, v[112:113], off
	global_load_dword v164, v[114:115], off
	global_load_dword v165, v[116:117], off
	global_load_dword v166, v[118:119], off
	global_load_dword v167, v[120:121], off
	global_load_dword v168, v[122:123], off
	global_load_dword v169, v[124:125], off
	global_load_dword v170, v[126:127], off
	global_load_dword v171, v[156:157], off
	v_or_b32_e32 v100, s46, v1
	v_or_b32_e32 v94, s47, v0
	s_add_i32 s40, s40, 16
	s_add_i32 s35, s35, 16
	s_add_i32 s41, s41, -16
	v_mad_u64_u32 v[94:95], s[44:45], v94, s53, v[4:5]
	v_mad_u64_u32 v[100:101], s[44:45], v100, s53, v[4:5]
	v_or_b32_e32 v95, s48, v1
	v_or_b32_e32 v101, s50, v0
	v_or_b32_e32 v108, s54, v1
	v_or_b32_e32 v106, s55, v0
	v_or_b32_e32 v112, s56, v1
	v_or_b32_e32 v110, s57, v0
	v_or_b32_e32 v116, s58, v1
	v_or_b32_e32 v114, s59, v0
	v_or_b32_e32 v120, s60, v1
	v_or_b32_e32 v118, s61, v0
	v_or_b32_e32 v124, s62, v1
	v_or_b32_e32 v122, s63, v0
	v_or_b32_e32 v156, s66, v1
	v_or_b32_e32 v126, s67, v0
	s_cmp_lg_u32 s41, 0
	v_mad_u64_u32 v[102:103], s[44:45], v101, s53, v[4:5]
	v_mad_u64_u32 v[104:105], s[44:45], v95, s53, v[4:5]
	v_mad_u64_u32 v[106:107], s[44:45], v106, s53, v[4:5]
	v_mad_u64_u32 v[108:109], s[44:45], v108, s53, v[4:5]
	v_mad_u64_u32 v[110:111], s[44:45], v110, s53, v[4:5]
	v_mad_u64_u32 v[112:113], s[44:45], v112, s53, v[4:5]
	v_mad_u64_u32 v[114:115], s[44:45], v114, s53, v[4:5]
	v_mad_u64_u32 v[116:117], s[44:45], v116, s53, v[4:5]
	v_mad_u64_u32 v[118:119], s[44:45], v118, s53, v[4:5]
	v_mad_u64_u32 v[120:121], s[44:45], v120, s53, v[4:5]
	v_mad_u64_u32 v[122:123], s[44:45], v122, s53, v[4:5]
	v_mad_u64_u32 v[124:125], s[44:45], v124, s53, v[4:5]
	v_mad_u64_u32 v[126:127], s[44:45], v126, s53, v[4:5]
	v_mad_u64_u32 v[156:157], s[44:45], v156, s53, v[4:5]
	s_nop 3
	s_lshl_b32 s46, s35, 1
	s_lshl_b32 s47, s40, 1
	v_or_b32_e32 v16, s46, v3
	v_or_b32_e32 v14, s47, v12
	s_add_i32 s48, s46, 4
	s_add_i32 s50, s47, 4
	s_add_i32 s54, s46, 8
	s_add_i32 s55, s47, 8
	s_add_i32 s56, s46, 12
	s_add_i32 s57, s47, 12
	s_add_i32 s58, s46, 16
	s_add_i32 s59, s47, 16
	s_add_i32 s60, s46, 20
	s_add_i32 s61, s47, 20
	s_add_i32 s62, s46, 24
	s_add_i32 s63, s47, 24
	s_add_i32 s66, s46, 28
	s_add_i32 s67, s47, 28
	v_mad_u64_u32 v[14:15], s[44:45], v14, s51, v[10:11]
	v_mad_u64_u32 v[22:23], s[44:45], v16, s51, v[10:11]
	v_or_b32_e32 v16, s48, v3
	v_or_b32_e32 v21, s50, v12
	v_or_b32_e32 v30, s54, v3
	v_or_b32_e32 v28, s55, v12
	v_or_b32_e32 v34, s56, v3
	v_or_b32_e32 v32, s57, v12
	v_or_b32_e32 v38, s58, v3
	v_or_b32_e32 v36, s59, v12
	v_or_b32_e32 v42, s60, v3
	v_or_b32_e32 v40, s61, v12
	v_or_b32_e32 v46, s62, v3
	v_or_b32_e32 v44, s63, v12
	v_or_b32_e32 v50, s66, v3
	v_or_b32_e32 v48, s67, v12
	v_mad_u64_u32 v[24:25], s[44:45], v21, s51, v[10:11]
	v_mad_u64_u32 v[26:27], s[44:45], v16, s51, v[10:11]
	v_mad_u64_u32 v[28:29], s[44:45], v28, s51, v[10:11]
	v_mad_u64_u32 v[30:31], s[44:45], v30, s51, v[10:11]
	v_mad_u64_u32 v[32:33], s[44:45], v32, s51, v[10:11]
	v_mad_u64_u32 v[34:35], s[44:45], v34, s51, v[10:11]
	v_mad_u64_u32 v[36:37], s[44:45], v36, s51, v[10:11]
	v_mad_u64_u32 v[38:39], s[44:45], v38, s51, v[10:11]
	v_mad_u64_u32 v[40:41], s[44:45], v40, s51, v[10:11]
	v_mad_u64_u32 v[42:43], s[44:45], v42, s51, v[10:11]
	v_mad_u64_u32 v[44:45], s[44:45], v44, s51, v[10:11]
	v_mad_u64_u32 v[46:47], s[44:45], v46, s51, v[10:11]
	v_mad_u64_u32 v[48:49], s[44:45], v48, s51, v[10:11]
	v_mad_u64_u32 v[50:51], s[44:45], v50, s51, v[10:11]
	global_load_dword v16, v[14:15], off
	global_load_dword v21, v[22:23], off
	global_load_dword v52, v[24:25], off
; #define LAS __attribute__((address_space(3)))
; DI unsigned pk2(float lo, float hi) { f32x2 v = {lo, hi}; return __builtin_bit_cast(unsigned, __builtin_convertvector(v, bf16x2v)); }
; #define LDS_WAIT() asm volatile("s_waitcnt lgkmcnt(0)" ::: "memory")
; DI void p0_transpose_item(const float* W, int K, int N, bf16_t* WT, int up_map, LAS float* scr, int item, int lane) {
;     ...
;     for (int i = 0; i < 32; ++i) { const int kk = 2 * i + (lane >> 5); scr[kk * 33 + (lane & 31)] = W[(size_t)(k0 + kk) * N + n0 + (lane & 31)]; }
;     LDS_WAIT(); asm volatile("" ::: "memory");
;     const int c = lane & 7;
; #pragma unroll
;     for (int j = 0; j < 4; ++j) { const int n = (lane >> 3) + 8 * j; const LAS float* s = scr + (8 * c) * 33 + n;
;         u32x4 o; o.x = pk2(s[0 * 33], s[1 * 33]); o.y = pk2(s[2 * 33], s[3 * 33]); o.z = pk2(s[4 * 33], s[5 * 33]); o.w = pk2(s[6 * 33], s[7 * 33]);
;         *(u32x4*)(WT + (size_t)(rowbase + n) * K + k0 + 8 * c) = o; }
;     LDS_WAIT(); asm volatile("" ::: "memory");
	global_load_dword v53, v[26:27], off
	global_load_dword v54, v[28:29], off
	global_load_dword v55, v[30:31], off
	global_load_dword v56, v[32:33], off
	global_load_dword v57, v[34:35], off
	global_load_dword v58, v[36:37], off
	global_load_dword v59, v[38:39], off
	global_load_dword v60, v[40:41], off
	global_load_dword v61, v[42:43], off
	global_load_dword v62, v[44:45], off
	global_load_dword v63, v[46:47], off
	global_load_dword v64, v[48:49], off
	global_load_dword v65, v[50:51], off
	v_or_b32_e32 v22, s46, v1
	v_or_b32_e32 v14, s47, v0
	s_add_i32 s40, s40, 16
	s_add_i32 s35, s35, 16
	s_add_i32 s41, s41, -16
	v_mad_u64_u32 v[14:15], s[44:45], v14, s53, v[4:5]
	v_mad_u64_u32 v[22:23], s[44:45], v22, s53, v[4:5]
	v_or_b32_e32 v15, s48, v1
	v_or_b32_e32 v23, s50, v0
	v_or_b32_e32 v30, s54, v1
	v_or_b32_e32 v28, s55, v0
	v_or_b32_e32 v34, s56, v1
	v_or_b32_e32 v32, s57, v0
	v_or_b32_e32 v38, s58, v1
	v_or_b32_e32 v36, s59, v0
	v_or_b32_e32 v42, s60, v1
	v_or_b32_e32 v40, s61, v0
	v_or_b32_e32 v46, s62, v1
	v_or_b32_e32 v44, s63, v0
	v_or_b32_e32 v50, s66, v1
	v_or_b32_e32 v48, s67, v0
	s_cmp_lg_u32 s41, 0
	v_mad_u64_u32 v[24:25], s[44:45], v23, s53, v[4:5]
	v_mad_u64_u32 v[26:27], s[44:45], v15, s53, v[4:5]
	v_mad_u64_u32 v[28:29], s[44:45], v28, s53, v[4:5]
	v_mad_u64_u32 v[30:31], s[44:45], v30, s53, v[4:5]
	v_mad_u64_u32 v[32:33], s[44:45], v32, s53, v[4:5]
	v_mad_u64_u32 v[34:35], s[44:45], v34, s53, v[4:5]
	v_mad_u64_u32 v[36:37], s[44:45], v36, s53, v[4:5]
	v_mad_u64_u32 v[38:39], s[44:45], v38, s53, v[4:5]
	v_mad_u64_u32 v[40:41], s[44:45], v40, s53, v[4:5]
	v_mad_u64_u32 v[42:43], s[44:45], v42, s53, v[4:5]
	v_mad_u64_u32 v[44:45], s[44:45], v44, s53, v[4:5]
	v_mad_u64_u32 v[46:47], s[44:45], v46, s53, v[4:5]
	v_mad_u64_u32 v[48:49], s[44:45], v48, s53, v[4:5]
	v_mad_u64_u32 v[50:51], s[44:45], v50, s53, v[4:5]
	s_waitcnt vmcnt(31)
	ds_write_b32 v94, v96
	s_waitcnt vmcnt(30)
	ds_write_b32 v100, v99
	s_waitcnt vmcnt(29)
	ds_write_b32 v102, v158
	s_waitcnt vmcnt(28)
	ds_write_b32 v104, v159
	s_waitcnt vmcnt(27)
	ds_write_b32 v106, v160
	s_waitcnt vmcnt(26)
	ds_write_b32 v108, v161
	s_waitcnt vmcnt(25)
	ds_write_b32 v110, v162
	s_waitcnt vmcnt(24)
	ds_write_b32 v112, v163
	s_waitcnt vmcnt(23)
	ds_write_b32 v114, v164
	s_waitcnt vmcnt(22)
	ds_write_b32 v116, v165
	s_waitcnt vmcnt(21)
	ds_write_b32 v118, v166
	s_waitcnt vmcnt(20)
	ds_write_b32 v120, v167
	s_waitcnt vmcnt(19)
	ds_write_b32 v122, v168
	s_waitcnt vmcnt(18)
	ds_write_b32 v124, v169
	s_waitcnt vmcnt(17)
	ds_write_b32 v126, v170
	s_waitcnt vmcnt(16)
	ds_write_b32 v156, v171
	s_waitcnt vmcnt(15)
	ds_write_b32 v14, v16
	s_waitcnt vmcnt(14)
	ds_write_b32 v22, v21
	s_waitcnt vmcnt(13)
	ds_write_b32 v24, v52
	s_waitcnt vmcnt(12)
	ds_write_b32 v26, v53
	s_waitcnt vmcnt(11)
	ds_write_b32 v28, v54
	s_waitcnt vmcnt(10)
	ds_write_b32 v30, v55
	s_waitcnt vmcnt(9)
	ds_write_b32 v32, v56
	s_waitcnt vmcnt(8)
	ds_write_b32 v34, v57
	s_waitcnt vmcnt(7)
	ds_write_b32 v36, v58
	s_waitcnt vmcnt(6)
	ds_write_b32 v38, v59
	s_waitcnt vmcnt(5)
	ds_write_b32 v40, v60
	s_waitcnt vmcnt(4)
	ds_write_b32 v42, v61
	s_waitcnt vmcnt(3)
	ds_write_b32 v44, v62
	s_waitcnt vmcnt(2)
	ds_write_b32 v46, v63
	s_waitcnt vmcnt(1)
	ds_write_b32 v48, v64
	s_waitcnt vmcnt(0)
	ds_write_b32 v50, v65
	s_waitcnt lgkmcnt(0)
	ds_read2_b32 v[14:15], v17 offset0:33 offset1:41
	ds_read2_b32 v[22:23], v17 offset1:8
	ds_read2_b32 v[24:25], v17 offset0:66 offset1:74
	ds_read2_b32 v[26:27], v17 offset0:99 offset1:107
	ds_read2_b32 v[28:29], v17 offset0:132 offset1:140
	ds_read2_b32 v[30:31], v17 offset0:165 offset1:173
	ds_read2_b32 v[32:33], v17 offset0:198 offset1:206
	ds_read2_b32 v[34:35], v17 offset0:231 offset1:239
	v_mov_b64_e32 v[10:11], s[8:9]
	s_mov_b32 s35, 0x2c00000
	v_mad_i64_i32 v[10:11], s[40:41], v8, s35, v[10:11]
	v_lshlrev_b32_e32 v184, 1, v13
	v_add_u32_e32 v38, v9, v7
	v_lshl_add_u64 v[10:11], v[10:11], 0, v[184:185]
	v_lshlrev_b32_e32 v184, 1, v6
	v_ashrrev_i32_e32 v39, 31, v38
	v_lshl_add_u64 v[36:37], v[10:11], 0, v[184:185]
	v_lshlrev_b64 v[38:39], 12, v[38:39]
	s_waitcnt lgkmcnt(6)
	v_cvt_pk_bf16_f32 v10, v22, v14
	s_waitcnt lgkmcnt(4)
	v_cvt_pk_bf16_f32 v11, v24, v26
	s_waitcnt lgkmcnt(2)
	v_cvt_pk_bf16_f32 v12, v28, v30
	s_waitcnt lgkmcnt(0)
	v_cvt_pk_bf16_f32 v13, v32, v34
	v_lshl_add_u64 v[38:39], v[36:37], 0, v[38:39]
	v_add_u32_e32 v14, v9, v18
	global_store_dwordx4 v[38:39], v[10:13], off
	v_add_u32_e32 v8, v9, v20
	v_readlane_b32 s66, v254, 13
	v_cvt_pk_bf16_f32 v10, v23, v15
	v_ashrrev_i32_e32 v15, 31, v14
	v_cvt_pk_bf16_f32 v11, v25, v27
	v_cvt_pk_bf16_f32 v12, v29, v31
	v_cvt_pk_bf16_f32 v13, v33, v35
	v_lshlrev_b64 v[14:15], 12, v[14:15]
	ds_read2_b32 v[22:23], v17 offset0:49 offset1:57
	ds_read2_b32 v[24:25], v17 offset0:16 offset1:24
	ds_read2_b32 v[26:27], v17 offset0:82 offset1:90
	ds_read2_b32 v[28:29], v17 offset0:115 offset1:123
	ds_read2_b32 v[30:31], v17 offset0:148 offset1:156
	ds_read2_b32 v[32:33], v17 offset0:181 offset1:189
	ds_read2_b32 v[34:35], v17 offset0:214 offset1:222
	ds_read2_b32 v[38:39], v17 offset0:247 offset1:255
	v_lshl_add_u64 v[14:15], v[36:37], 0, v[14:15]
	global_store_dwordx4 v[14:15], v[10:13], off
	v_add_u32_e32 v14, v9, v19
	v_ashrrev_i32_e32 v15, 31, v14
	v_lshlrev_b64 v[14:15], 12, v[14:15]
	v_ashrrev_i32_e32 v9, 31, v8
	s_waitcnt lgkmcnt(6)
	v_cvt_pk_bf16_f32 v10, v24, v22
	s_waitcnt lgkmcnt(4)
	v_cvt_pk_bf16_f32 v11, v26, v28
	s_waitcnt lgkmcnt(2)
	v_cvt_pk_bf16_f32 v12, v30, v32
	s_waitcnt lgkmcnt(0)
	v_cvt_pk_bf16_f32 v13, v34, v38
	v_lshl_add_u64 v[14:15], v[36:37], 0, v[14:15]
	v_lshlrev_b64 v[8:9], 12, v[8:9]
	global_store_dwordx4 v[14:15], v[10:13], off
	v_lshl_add_u64 v[8:9], v[36:37], 0, v[8:9]
	v_readlane_b32 s62, v254, 14
	v_cvt_pk_bf16_f32 v10, v25, v23
	v_cvt_pk_bf16_f32 v11, v27, v29
	v_cvt_pk_bf16_f32 v12, v31, v33
	v_cvt_pk_bf16_f32 v13, v35, v39
	global_store_dwordx4 v[8:9], v[10:13], off
	s_waitcnt lgkmcnt(0)
	s_movk_i32 s63, 0x7fff
	v_readlane_b32 s67, v254, 15
	s_or_b64 exec, exec, s[38:39]

; DI void p0_transpose_item(const float* W, int K, int N, bf16_t* WT, int up_map, LAS float* scr, int item, int lane) {
;     ...
; #pragma unroll 8
;     for (int i = 0; i < 32; ++i) { const int kk = 2 * i + (lane >> 5); scr[kk * 33 + (lane & 31)] = W[(size_t)(k0 + kk) * N + n0 + (lane & 31)]; }
.LBB0_814:
	s_lshl_b32 s40, s35, 1
	s_lshl_b32 s41, s38, 1
	v_or_b32_e32 v184, s41, v14
	s_add_i32 s44, s40, 4
	s_add_i32 s45, s41, 4
	v_mov_b32_e32 v103, v185
	s_add_i32 s47, s41, 8
	v_lshlrev_b64 v[116:117], 13, v[184:185]
	v_or_b32_e32 v102, s44, v3
	v_or_b32_e32 v184, s45, v14
	v_mov_b32_e32 v101, v185
	v_or_b32_e32 v100, s40, v3
	s_add_i32 s50, s41, 12
	v_lshlrev_b64 v[102:103], 13, v[102:103]
	v_lshlrev_b64 v[118:119], 13, v[184:185]
	v_or_b32_e32 v184, s47, v14
	s_add_i32 s46, s40, 8
	s_add_i32 s48, s40, 12
	s_add_i32 s55, s41, 16
	v_lshlrev_b64 v[100:101], 13, v[100:101]
	v_lshl_add_u64 v[116:117], v[12:13], 0, v[116:117]
	v_lshl_add_u64 v[102:103], v[12:13], 0, v[102:103]
	v_lshlrev_b64 v[120:121], 13, v[184:185]
	v_or_b32_e32 v184, s50, v14
	v_mov_b32_e32 v105, v185
	v_mov_b32_e32 v107, v185
	s_add_i32 s57, s41, 20
	v_or_b32_e32 v104, s46, v3
	v_or_b32_e32 v106, s48, v3
	v_lshl_add_u64 v[100:101], v[12:13], 0, v[100:101]
	v_lshl_add_u64 v[118:119], v[12:13], 0, v[118:119]
	global_load_dword v95, v[116:117], off
	global_load_dword v96, v[100:101], off
	global_load_dword v99, v[118:119], off
	global_load_dword v160, v[102:103], off
	v_lshlrev_b64 v[102:103], 13, v[184:185]
	v_or_b32_e32 v184, s55, v14
	s_add_i32 s54, s40, 16
	s_add_i32 s56, s40, 20
	s_add_i32 s59, s41, 24
	v_lshlrev_b64 v[104:105], 13, v[104:105]
	v_lshlrev_b64 v[106:107], 13, v[106:107]
	v_lshl_add_u64 v[100:101], v[12:13], 0, v[120:121]
	v_lshl_add_u64 v[102:103], v[12:13], 0, v[102:103]
	v_lshlrev_b64 v[116:117], 13, v[184:185]
	v_or_b32_e32 v184, s57, v14
	v_mov_b32_e32 v109, v185
	v_mov_b32_e32 v111, v185
	s_add_i32 s58, s40, 24
	s_add_i32 s60, s40, 28
	s_add_i32 s61, s41, 28
	v_or_b32_e32 v108, s54, v3
	v_or_b32_e32 v110, s56, v3
	v_lshl_add_u64 v[104:105], v[12:13], 0, v[104:105]
	v_lshl_add_u64 v[106:107], v[12:13], 0, v[106:107]
	global_load_dword v161, v[100:101], off
	global_load_dword v162, v[104:105], off
	global_load_dword v163, v[102:103], off
	global_load_dword v164, v[106:107], off
	v_lshlrev_b64 v[102:103], 13, v[184:185]
	v_or_b32_e32 v184, s59, v14
	v_mov_b32_e32 v113, v185
	v_mov_b32_e32 v115, v185
	v_or_b32_e32 v112, s58, v3
	v_or_b32_e32 v114, s60, v3
	v_lshlrev_b64 v[108:109], 13, v[108:109]
	v_lshlrev_b64 v[110:111], 13, v[110:111]
	v_lshl_add_u64 v[100:101], v[12:13], 0, v[116:117]
	v_lshl_add_u64 v[102:103], v[12:13], 0, v[102:103]
	v_lshlrev_b64 v[104:105], 13, v[184:185]
	v_or_b32_e32 v184, s61, v14
	v_lshlrev_b64 v[112:113], 13, v[112:113]
	v_lshlrev_b64 v[114:115], 13, v[114:115]
	v_lshl_add_u64 v[108:109], v[12:13], 0, v[108:109]
	v_lshl_add_u64 v[110:111], v[12:13], 0, v[110:111]
	global_load_dword v165, v[100:101], off
	global_load_dword v166, v[108:109], off
	global_load_dword v167, v[102:103], off
	global_load_dword v168, v[110:111], off
	v_lshl_add_u64 v[100:101], v[12:13], 0, v[104:105]
	v_lshlrev_b64 v[102:103], 13, v[184:185]
	v_lshl_add_u64 v[112:113], v[12:13], 0, v[112:113]
	v_lshl_add_u64 v[114:115], v[12:13], 0, v[114:115]
	v_lshl_add_u64 v[102:103], v[12:13], 0, v[102:103]
	global_load_dword v169, v[100:101], off
	global_load_dword v170, v[112:113], off
	global_load_dword v171, v[102:103], off
	global_load_dword v172, v[114:115], off
	v_or_b32_e32 v102, s40, v1
	v_or_b32_e32 v100, s41, v0
	s_add_i32 s38, s38, 16
	s_add_i32 s35, s35, 16
	s_add_i32 s39, s39, -16
	v_mad_u64_u32 v[100:101], s[40:41], v100, s53, v[4:5]
	v_mad_u64_u32 v[102:103], s[40:41], v102, s53, v[4:5]
	v_or_b32_e32 v101, s44, v1
	v_or_b32_e32 v103, s45, v0
	v_or_b32_e32 v110, s46, v1
	v_or_b32_e32 v108, s47, v0
	v_or_b32_e32 v114, s48, v1
	v_or_b32_e32 v112, s50, v0
	v_or_b32_e32 v118, s54, v1
	v_or_b32_e32 v116, s55, v0
	v_or_b32_e32 v122, s56, v1
	v_or_b32_e32 v120, s57, v0
	v_or_b32_e32 v126, s58, v1
	v_or_b32_e32 v124, s59, v0
	v_or_b32_e32 v158, s60, v1
	v_or_b32_e32 v156, s61, v0
	s_cmp_lg_u32 s39, 0
	v_mad_u64_u32 v[104:105], s[40:41], v103, s53, v[4:5]
	v_mad_u64_u32 v[106:107], s[40:41], v101, s53, v[4:5]
	v_mad_u64_u32 v[108:109], s[40:41], v108, s53, v[4:5]
	v_mad_u64_u32 v[110:111], s[40:41], v110, s53, v[4:5]
	v_mad_u64_u32 v[112:113], s[40:41], v112, s53, v[4:5]
	v_mad_u64_u32 v[114:115], s[40:41], v114, s53, v[4:5]
	v_mad_u64_u32 v[116:117], s[40:41], v116, s53, v[4:5]
	v_mad_u64_u32 v[118:119], s[40:41], v118, s53, v[4:5]
	v_mad_u64_u32 v[120:121], s[40:41], v120, s53, v[4:5]
	v_mad_u64_u32 v[122:123], s[40:41], v122, s53, v[4:5]
	v_mad_u64_u32 v[124:125], s[40:41], v124, s53, v[4:5]
	v_mad_u64_u32 v[126:127], s[40:41], v126, s53, v[4:5]
	v_mad_u64_u32 v[156:157], s[40:41], v156, s53, v[4:5]
	v_mad_u64_u32 v[158:159], s[40:41], v158, s53, v[4:5]
	s_nop 3
	s_lshl_b32 s40, s35, 1
	s_lshl_b32 s41, s38, 1
	v_or_b32_e32 v184, s41, v14
	s_add_i32 s44, s40, 4
	s_add_i32 s45, s41, 4
	v_mov_b32_e32 v25, v185
	s_add_i32 s47, s41, 8
	v_lshlrev_b64 v[38:39], 13, v[184:185]
	v_or_b32_e32 v24, s44, v3
	v_or_b32_e32 v184, s45, v14
	v_mov_b32_e32 v23, v185
	v_or_b32_e32 v22, s40, v3
	s_add_i32 s50, s41, 12
	v_lshlrev_b64 v[24:25], 13, v[24:25]
	v_lshlrev_b64 v[40:41], 13, v[184:185]
	v_or_b32_e32 v184, s47, v14
	s_add_i32 s46, s40, 8
	s_add_i32 s48, s40, 12
	s_add_i32 s55, s41, 16
	v_lshlrev_b64 v[22:23], 13, v[22:23]
	v_lshl_add_u64 v[38:39], v[12:13], 0, v[38:39]
	v_lshl_add_u64 v[24:25], v[12:13], 0, v[24:25]
	v_lshlrev_b64 v[42:43], 13, v[184:185]
	v_or_b32_e32 v184, s50, v14
	v_mov_b32_e32 v27, v185
	v_mov_b32_e32 v29, v185
	s_add_i32 s57, s41, 20
	v_or_b32_e32 v26, s46, v3
	v_or_b32_e32 v28, s48, v3
	v_lshl_add_u64 v[22:23], v[12:13], 0, v[22:23]
	v_lshl_add_u64 v[40:41], v[12:13], 0, v[40:41]
	global_load_dword v9, v[38:39], off
; DI void p0_transpose_item(const float* W, int K, int N, bf16_t* WT, int up_map, LAS float* scr, int item, int lane) {
;     ...
;     for (int i = 0; i < 32; ++i) { const int kk = 2 * i + (lane >> 5); scr[kk * 33 + (lane & 31)] = W[(size_t)(k0 + kk) * N + n0 + (lane & 31)]; }
	global_load_dword v16, v[22:23], off
	global_load_dword v21, v[40:41], off
	global_load_dword v54, v[24:25], off
	v_lshlrev_b64 v[24:25], 13, v[184:185]
	v_or_b32_e32 v184, s55, v14
	s_add_i32 s54, s40, 16
	s_add_i32 s56, s40, 20
	s_add_i32 s59, s41, 24
	v_lshlrev_b64 v[26:27], 13, v[26:27]
	v_lshlrev_b64 v[28:29], 13, v[28:29]
	v_lshl_add_u64 v[22:23], v[12:13], 0, v[42:43]
	v_lshl_add_u64 v[24:25], v[12:13], 0, v[24:25]
	v_lshlrev_b64 v[38:39], 13, v[184:185]
	v_or_b32_e32 v184, s57, v14
	v_mov_b32_e32 v31, v185
	v_mov_b32_e32 v33, v185
	s_add_i32 s58, s40, 24
	s_add_i32 s60, s40, 28
	s_add_i32 s61, s41, 28
	v_or_b32_e32 v30, s54, v3
	v_or_b32_e32 v32, s56, v3
	v_lshl_add_u64 v[26:27], v[12:13], 0, v[26:27]
	v_lshl_add_u64 v[28:29], v[12:13], 0, v[28:29]
	global_load_dword v55, v[22:23], off
	global_load_dword v56, v[26:27], off
	global_load_dword v57, v[24:25], off
	global_load_dword v58, v[28:29], off
	v_lshlrev_b64 v[24:25], 13, v[184:185]
	v_or_b32_e32 v184, s59, v14
	v_mov_b32_e32 v35, v185
	v_mov_b32_e32 v37, v185
	v_or_b32_e32 v34, s58, v3
	v_or_b32_e32 v36, s60, v3
	v_lshlrev_b64 v[30:31], 13, v[30:31]
	v_lshlrev_b64 v[32:33], 13, v[32:33]
	v_lshl_add_u64 v[22:23], v[12:13], 0, v[38:39]
	v_lshl_add_u64 v[24:25], v[12:13], 0, v[24:25]
	v_lshlrev_b64 v[26:27], 13, v[184:185]
	v_or_b32_e32 v184, s61, v14
	v_lshlrev_b64 v[34:35], 13, v[34:35]
	v_lshlrev_b64 v[36:37], 13, v[36:37]
	v_lshl_add_u64 v[30:31], v[12:13], 0, v[30:31]
	v_lshl_add_u64 v[32:33], v[12:13], 0, v[32:33]
	global_load_dword v59, v[22:23], off
	global_load_dword v60, v[30:31], off
	global_load_dword v61, v[24:25], off
	global_load_dword v62, v[32:33], off
	v_lshl_add_u64 v[22:23], v[12:13], 0, v[26:27]
	v_lshlrev_b64 v[24:25], 13, v[184:185]
	v_lshl_add_u64 v[34:35], v[12:13], 0, v[34:35]
	v_lshl_add_u64 v[36:37], v[12:13], 0, v[36:37]
	v_lshl_add_u64 v[24:25], v[12:13], 0, v[24:25]
	global_load_dword v63, v[22:23], off
	global_load_dword v64, v[34:35], off
	global_load_dword v65, v[24:25], off
	global_load_dword v66, v[36:37], off
	v_or_b32_e32 v24, s40, v1
	v_or_b32_e32 v22, s41, v0
	s_add_i32 s38, s38, 16
	s_add_i32 s35, s35, 16
	s_add_i32 s39, s39, -16
	v_mad_u64_u32 v[22:23], s[40:41], v22, s53, v[4:5]
	v_mad_u64_u32 v[24:25], s[40:41], v24, s53, v[4:5]
	v_or_b32_e32 v23, s44, v1
	v_or_b32_e32 v25, s45, v0
	v_or_b32_e32 v32, s46, v1
	v_or_b32_e32 v30, s47, v0
	v_or_b32_e32 v36, s48, v1
	v_or_b32_e32 v34, s50, v0
	v_or_b32_e32 v40, s54, v1
	v_or_b32_e32 v38, s55, v0
	v_or_b32_e32 v44, s56, v1
	v_or_b32_e32 v42, s57, v0
	v_or_b32_e32 v48, s58, v1
	v_or_b32_e32 v46, s59, v0
	v_or_b32_e32 v52, s60, v1
	v_or_b32_e32 v50, s61, v0
	s_cmp_lg_u32 s39, 0
	v_mad_u64_u32 v[26:27], s[40:41], v25, s53, v[4:5]
	v_mad_u64_u32 v[28:29], s[40:41], v23, s53, v[4:5]
	v_mad_u64_u32 v[30:31], s[40:41], v30, s53, v[4:5]
	v_mad_u64_u32 v[32:33], s[40:41], v32, s53, v[4:5]
	v_mad_u64_u32 v[34:35], s[40:41], v34, s53, v[4:5]
	v_mad_u64_u32 v[36:37], s[40:41], v36, s53, v[4:5]
	v_mad_u64_u32 v[38:39], s[40:41], v38, s53, v[4:5]
	v_mad_u64_u32 v[40:41], s[40:41], v40, s53, v[4:5]
	v_mad_u64_u32 v[42:43], s[40:41], v42, s53, v[4:5]
	v_mad_u64_u32 v[44:45], s[40:41], v44, s53, v[4:5]
	v_mad_u64_u32 v[46:47], s[40:41], v46, s53, v[4:5]
	v_mad_u64_u32 v[48:49], s[40:41], v48, s53, v[4:5]
	v_mad_u64_u32 v[50:51], s[40:41], v50, s53, v[4:5]
	v_mad_u64_u32 v[52:53], s[40:41], v52, s53, v[4:5]
	s_waitcnt vmcnt(31)
	ds_write_b32 v100, v95
	s_waitcnt vmcnt(30)
	ds_write_b32 v102, v96
	s_waitcnt vmcnt(29)
	ds_write_b32 v104, v99
	s_waitcnt vmcnt(28)
	ds_write_b32 v106, v160
	s_waitcnt vmcnt(27)
; #define LAS __attribute__((address_space(3)))
; DI unsigned pk2(float lo, float hi) { f32x2 v = {lo, hi}; return __builtin_bit_cast(unsigned, __builtin_convertvector(v, bf16x2v)); }
; #define LDS_WAIT() asm volatile("s_waitcnt lgkmcnt(0)" ::: "memory")
; DI void p0_transpose_item(const float* W, int K, int N, bf16_t* WT, int up_map, LAS float* scr, int item, int lane) {
;     ...
;     for (int i = 0; i < 32; ++i) { const int kk = 2 * i + (lane >> 5); scr[kk * 33 + (lane & 31)] = W[(size_t)(k0 + kk) * N + n0 + (lane & 31)]; }
;     LDS_WAIT(); asm volatile("" ::: "memory");
;     const int c = lane & 7;
; #pragma unroll
;     for (int j = 0; j < 4; ++j) { const int n = (lane >> 3) + 8 * j; const LAS float* s = scr + (8 * c) * 33 + n;
;         u32x4 o; o.x = pk2(s[0 * 33], s[1 * 33]); o.y = pk2(s[2 * 33], s[3 * 33]); o.z = pk2(s[4 * 33], s[5 * 33]); o.w = pk2(s[6 * 33], s[7 * 33]);
;         *(u32x4*)(WT + (size_t)(rowbase + n) * K + k0 + 8 * c) = o; }
;     LDS_WAIT(); asm volatile("" ::: "memory");
	ds_write_b32 v108, v161
	s_waitcnt vmcnt(26)
	ds_write_b32 v110, v162
	s_waitcnt vmcnt(25)
	ds_write_b32 v112, v163
	s_waitcnt vmcnt(24)
	ds_write_b32 v114, v164
	s_waitcnt vmcnt(23)
	ds_write_b32 v116, v165
	s_waitcnt vmcnt(22)
	ds_write_b32 v118, v166
	s_waitcnt vmcnt(21)
	ds_write_b32 v120, v167
	s_waitcnt vmcnt(20)
	ds_write_b32 v122, v168
	s_waitcnt vmcnt(19)
	ds_write_b32 v124, v169
	s_waitcnt vmcnt(18)
	ds_write_b32 v126, v170
	s_waitcnt vmcnt(17)
	ds_write_b32 v156, v171
	s_waitcnt vmcnt(16)
	ds_write_b32 v158, v172
	s_waitcnt vmcnt(15)
	ds_write_b32 v22, v9
	s_waitcnt vmcnt(14)
	ds_write_b32 v24, v16
	s_waitcnt vmcnt(13)
	ds_write_b32 v26, v21
	s_waitcnt vmcnt(12)
	ds_write_b32 v28, v54
	s_waitcnt vmcnt(11)
	ds_write_b32 v30, v55
	s_waitcnt vmcnt(10)
	ds_write_b32 v32, v56
	s_waitcnt vmcnt(9)
	ds_write_b32 v34, v57
	s_waitcnt vmcnt(8)
	ds_write_b32 v36, v58
	s_waitcnt vmcnt(7)
	ds_write_b32 v38, v59
	s_waitcnt vmcnt(6)
	ds_write_b32 v40, v60
	s_waitcnt vmcnt(5)
	ds_write_b32 v42, v61
	s_waitcnt vmcnt(4)
	ds_write_b32 v44, v62
	s_waitcnt vmcnt(3)
	ds_write_b32 v46, v63
	s_waitcnt vmcnt(2)
	ds_write_b32 v48, v64
	s_waitcnt vmcnt(1)
	ds_write_b32 v50, v65
	s_waitcnt vmcnt(0)
	ds_write_b32 v52, v66
	s_waitcnt lgkmcnt(0)
	ds_read2_b32 v[12:13], v17 offset0:33 offset1:41
	ds_read2_b32 v[22:23], v17 offset1:8
	ds_read2_b32 v[24:25], v17 offset0:66 offset1:74
	ds_read2_b32 v[26:27], v17 offset0:99 offset1:107
	ds_read2_b32 v[28:29], v17 offset0:132 offset1:140
	ds_read2_b32 v[30:31], v17 offset0:165 offset1:173
	ds_read2_b32 v[32:33], v17 offset0:198 offset1:206
	ds_read2_b32 v[34:35], v17 offset0:231 offset1:239
	v_lshl_add_u64 v[10:11], v[10:11], 1, s[10:11]
	v_mov_b32_e32 v9, v185
	v_lshl_add_u64 v[8:9], v[8:9], 1, v[10:11]
	v_lshlrev_b32_e32 v184, 1, v6
	v_or_b32_e32 v3, v15, v7
	v_lshl_add_u64 v[36:37], v[8:9], 0, v[184:185]
	v_lshlrev_b32_e32 v184, 12, v3
	s_waitcnt lgkmcnt(6)
	v_cvt_pk_bf16_f32 v8, v22, v12
	s_waitcnt lgkmcnt(4)
	v_cvt_pk_bf16_f32 v9, v24, v26
	s_waitcnt lgkmcnt(2)
	v_cvt_pk_bf16_f32 v10, v28, v30
	s_waitcnt lgkmcnt(0)
	v_cvt_pk_bf16_f32 v11, v32, v34
	v_lshl_add_u64 v[38:39], v[36:37], 0, v[184:185]
	global_store_dwordx4 v[38:39], v[8:11], off
	v_or_b32_e32 v3, v15, v18
	v_lshlrev_b32_e32 v184, 12, v3
	v_cvt_pk_bf16_f32 v8, v23, v13
	v_cvt_pk_bf16_f32 v9, v25, v27
	v_cvt_pk_bf16_f32 v10, v29, v31
	v_cvt_pk_bf16_f32 v11, v33, v35
	ds_read2_b32 v[22:23], v17 offset0:49 offset1:57
	ds_read2_b32 v[24:25], v17 offset0:16 offset1:24
	ds_read2_b32 v[26:27], v17 offset0:82 offset1:90
	ds_read2_b32 v[28:29], v17 offset0:115 offset1:123
	ds_read2_b32 v[30:31], v17 offset0:148 offset1:156
	ds_read2_b32 v[32:33], v17 offset0:181 offset1:189
	ds_read2_b32 v[34:35], v17 offset0:214 offset1:222
	ds_read2_b32 v[38:39], v17 offset0:247 offset1:255
	v_or_b32_e32 v3, v15, v19
	v_lshl_add_u64 v[12:13], v[36:37], 0, v[184:185]
	v_lshlrev_b32_e32 v184, 12, v3
	v_or_b32_e32 v3, v15, v20
	global_store_dwordx4 v[12:13], v[8:11], off
	v_lshl_add_u64 v[12:13], v[36:37], 0, v[184:185]
	v_lshlrev_b32_e32 v184, 12, v3
	s_waitcnt lgkmcnt(6)
	v_cvt_pk_bf16_f32 v8, v24, v22
	s_waitcnt lgkmcnt(4)
	v_cvt_pk_bf16_f32 v9, v26, v28
	s_waitcnt lgkmcnt(2)
	v_cvt_pk_bf16_f32 v10, v30, v32
	s_waitcnt lgkmcnt(0)
	v_cvt_pk_bf16_f32 v11, v34, v38
	global_store_dwordx4 v[12:13], v[8:11], off
	v_lshl_add_u64 v[12:13], v[36:37], 0, v[184:185]
	s_nop 0
	v_cvt_pk_bf16_f32 v8, v25, v23
	v_cvt_pk_bf16_f32 v9, v27, v29
	v_cvt_pk_bf16_f32 v10, v31, v33
	v_cvt_pk_bf16_f32 v11, v35, v39
	global_store_dwordx4 v[12:13], v[8:11], off
	s_waitcnt lgkmcnt(0)

; DI void p0_transpose_item(const float* W, int K, int N, bf16_t* WT, int up_map, LAS float* scr, int item, int lane) {
;     ...
; #pragma unroll 8
;     for (int i = 0; i < 32; ++i) { const int kk = 2 * i + (lane >> 5); scr[kk * 33 + (lane & 31)] = W[(size_t)(k0 + kk) * N + n0 + (lane & 31)]; }
.LBB0_819:
	s_lshl_b32 s38, s35, 1
	s_lshl_b32 s39, s36, 1
	v_or_b32_e32 v102, s39, v16
	s_add_i32 s40, s38, 4
	s_add_i32 s41, s39, 4
	s_add_i32 s44, s38, 8
	s_add_i32 s45, s39, 8
	s_add_i32 s46, s38, 12
	s_add_i32 s47, s39, 12
	s_add_i32 s48, s38, 16
	s_add_i32 s50, s39, 16
	s_add_i32 s54, s38, 20
	s_add_i32 s55, s39, 20
	s_add_i32 s56, s38, 24
	s_add_i32 s57, s39, 24
	s_add_i32 s58, s38, 28
	s_add_i32 s59, s39, 28
	v_or_b32_e32 v100, s38, v3
	v_ashrrev_i32_e32 v103, 31, v102
	v_or_b32_e32 v104, s40, v3
	v_or_b32_e32 v106, s41, v16
	v_or_b32_e32 v108, s44, v3
	v_or_b32_e32 v110, s45, v16
	v_or_b32_e32 v112, s46, v3
	v_or_b32_e32 v114, s47, v16
	v_or_b32_e32 v116, s48, v3
	v_or_b32_e32 v118, s50, v16
	v_or_b32_e32 v120, s54, v3
	v_or_b32_e32 v122, s55, v16
	v_or_b32_e32 v124, s56, v3
	v_or_b32_e32 v126, s57, v16
	v_or_b32_e32 v156, s58, v3
	v_or_b32_e32 v158, s59, v16
	v_ashrrev_i32_e32 v101, 31, v100
	v_lshlrev_b64 v[102:103], 14, v[102:103]
	v_ashrrev_i32_e32 v107, 31, v106
	v_ashrrev_i32_e32 v105, 31, v104
	v_ashrrev_i32_e32 v111, 31, v110
	v_ashrrev_i32_e32 v109, 31, v108
	v_ashrrev_i32_e32 v115, 31, v114
	v_ashrrev_i32_e32 v113, 31, v112
	v_ashrrev_i32_e32 v119, 31, v118
	v_ashrrev_i32_e32 v117, 31, v116
	v_ashrrev_i32_e32 v123, 31, v122
	v_ashrrev_i32_e32 v121, 31, v120
	v_ashrrev_i32_e32 v127, 31, v126
	v_ashrrev_i32_e32 v125, 31, v124
	v_ashrrev_i32_e32 v159, 31, v158
	v_ashrrev_i32_e32 v157, 31, v156
	v_lshlrev_b64 v[100:101], 14, v[100:101]
	v_lshl_add_u64 v[102:103], v[14:15], 0, v[102:103]
	v_lshlrev_b64 v[104:105], 14, v[104:105]
	v_lshlrev_b64 v[106:107], 14, v[106:107]
	v_lshlrev_b64 v[108:109], 14, v[108:109]
	v_lshlrev_b64 v[110:111], 14, v[110:111]
	v_lshlrev_b64 v[112:113], 14, v[112:113]
	v_lshlrev_b64 v[114:115], 14, v[114:115]
	v_lshlrev_b64 v[116:117], 14, v[116:117]
	v_lshlrev_b64 v[118:119], 14, v[118:119]
	v_lshlrev_b64 v[120:121], 14, v[120:121]
	v_lshlrev_b64 v[122:123], 14, v[122:123]
	v_lshlrev_b64 v[124:125], 14, v[124:125]
	v_lshlrev_b64 v[126:127], 14, v[126:127]
	v_lshlrev_b64 v[156:157], 14, v[156:157]
	v_lshlrev_b64 v[158:159], 14, v[158:159]
	v_lshl_add_u64 v[100:101], v[14:15], 0, v[100:101]
	v_lshl_add_u64 v[106:107], v[14:15], 0, v[106:107]
	v_lshl_add_u64 v[104:105], v[14:15], 0, v[104:105]
	v_lshl_add_u64 v[110:111], v[14:15], 0, v[110:111]
	v_lshl_add_u64 v[108:109], v[14:15], 0, v[108:109]
	v_lshl_add_u64 v[114:115], v[14:15], 0, v[114:115]
	v_lshl_add_u64 v[112:113], v[14:15], 0, v[112:113]
	v_lshl_add_u64 v[118:119], v[14:15], 0, v[118:119]
	v_lshl_add_u64 v[116:117], v[14:15], 0, v[116:117]
	v_lshl_add_u64 v[122:123], v[14:15], 0, v[122:123]
	v_lshl_add_u64 v[120:121], v[14:15], 0, v[120:121]
	v_lshl_add_u64 v[126:127], v[14:15], 0, v[126:127]
	v_lshl_add_u64 v[124:125], v[14:15], 0, v[124:125]
	v_lshl_add_u64 v[158:159], v[14:15], 0, v[158:159]
	v_lshl_add_u64 v[156:157], v[14:15], 0, v[156:157]
	global_load_dword v95, v[102:103], off
	global_load_dword v97, v[100:101], off
	global_load_dword v99, v[106:107], off
	global_load_dword v160, v[104:105], off
	global_load_dword v161, v[110:111], off
	global_load_dword v162, v[108:109], off
	global_load_dword v163, v[114:115], off
	global_load_dword v164, v[112:113], off
	global_load_dword v165, v[118:119], off
	global_load_dword v166, v[116:117], off
	global_load_dword v167, v[122:123], off
	global_load_dword v168, v[120:121], off
	global_load_dword v169, v[126:127], off
	global_load_dword v170, v[124:125], off
	global_load_dword v171, v[158:159], off
	global_load_dword v172, v[156:157], off
	v_or_b32_e32 v102, s38, v1
	v_or_b32_e32 v100, s39, v0
	s_add_i32 s36, s36, 16
	s_add_i32 s35, s35, 16
	s_add_i32 s37, s37, -16
	v_mad_u64_u32 v[100:101], s[38:39], v100, s53, v[4:5]
	v_mad_u64_u32 v[102:103], s[38:39], v102, s53, v[4:5]
	v_or_b32_e32 v101, s40, v1
	v_or_b32_e32 v103, s41, v0
	v_or_b32_e32 v110, s44, v1
	v_or_b32_e32 v108, s45, v0
	v_or_b32_e32 v114, s46, v1
	v_or_b32_e32 v112, s47, v0
	v_or_b32_e32 v118, s48, v1
	v_or_b32_e32 v116, s50, v0
	v_or_b32_e32 v122, s54, v1
	v_or_b32_e32 v120, s55, v0
	v_or_b32_e32 v126, s56, v1
	v_or_b32_e32 v124, s57, v0
	v_or_b32_e32 v158, s58, v1
	v_or_b32_e32 v156, s59, v0
	s_cmp_lg_u32 s37, 0
	v_mad_u64_u32 v[104:105], s[38:39], v103, s53, v[4:5]
	v_mad_u64_u32 v[106:107], s[38:39], v101, s53, v[4:5]
	v_mad_u64_u32 v[108:109], s[38:39], v108, s53, v[4:5]
	v_mad_u64_u32 v[110:111], s[38:39], v110, s53, v[4:5]
	v_mad_u64_u32 v[112:113], s[38:39], v112, s53, v[4:5]
	v_mad_u64_u32 v[114:115], s[38:39], v114, s53, v[4:5]
	v_mad_u64_u32 v[116:117], s[38:39], v116, s53, v[4:5]
	v_mad_u64_u32 v[118:119], s[38:39], v118, s53, v[4:5]
	v_mad_u64_u32 v[120:121], s[38:39], v120, s53, v[4:5]
	v_mad_u64_u32 v[122:123], s[38:39], v122, s53, v[4:5]
	v_mad_u64_u32 v[124:125], s[38:39], v124, s53, v[4:5]
	v_mad_u64_u32 v[126:127], s[38:39], v126, s53, v[4:5]
	v_mad_u64_u32 v[156:157], s[38:39], v156, s53, v[4:5]
	v_mad_u64_u32 v[158:159], s[38:39], v158, s53, v[4:5]
	s_nop 3
	s_lshl_b32 s38, s35, 1
	s_lshl_b32 s39, s36, 1
	v_or_b32_e32 v24, s39, v16
	s_add_i32 s40, s38, 4
	s_add_i32 s41, s39, 4
	s_add_i32 s44, s38, 8
	s_add_i32 s45, s39, 8
	s_add_i32 s46, s38, 12
	s_add_i32 s47, s39, 12
	s_add_i32 s48, s38, 16
	s_add_i32 s50, s39, 16
	s_add_i32 s54, s38, 20
	s_add_i32 s55, s39, 20
	s_add_i32 s56, s38, 24
	s_add_i32 s57, s39, 24
	s_add_i32 s58, s38, 28
	s_add_i32 s59, s39, 28
	v_or_b32_e32 v22, s38, v3
	v_ashrrev_i32_e32 v25, 31, v24
	v_or_b32_e32 v26, s40, v3
	v_or_b32_e32 v28, s41, v16
	v_or_b32_e32 v30, s44, v3
	v_or_b32_e32 v32, s45, v16
	v_or_b32_e32 v34, s46, v3
	v_or_b32_e32 v36, s47, v16
	v_or_b32_e32 v38, s48, v3
; DI void p0_transpose_item(const float* W, int K, int N, bf16_t* WT, int up_map, LAS float* scr, int item, int lane) {
;     ...
;     for (int i = 0; i < 32; ++i) { const int kk = 2 * i + (lane >> 5); scr[kk * 33 + (lane & 31)] = W[(size_t)(k0 + kk) * N + n0 + (lane & 31)]; }
	v_or_b32_e32 v40, s50, v16
	v_or_b32_e32 v42, s54, v3
	v_or_b32_e32 v44, s55, v16
	v_or_b32_e32 v46, s56, v3
	v_or_b32_e32 v48, s57, v16
	v_or_b32_e32 v50, s58, v3
	v_or_b32_e32 v52, s59, v16
	v_ashrrev_i32_e32 v23, 31, v22
	v_lshlrev_b64 v[24:25], 14, v[24:25]
	v_ashrrev_i32_e32 v29, 31, v28
	v_ashrrev_i32_e32 v27, 31, v26
	v_ashrrev_i32_e32 v33, 31, v32
	v_ashrrev_i32_e32 v31, 31, v30
	v_ashrrev_i32_e32 v37, 31, v36
	v_ashrrev_i32_e32 v35, 31, v34
	v_ashrrev_i32_e32 v41, 31, v40
	v_ashrrev_i32_e32 v39, 31, v38
	v_ashrrev_i32_e32 v45, 31, v44
	v_ashrrev_i32_e32 v43, 31, v42
	v_ashrrev_i32_e32 v49, 31, v48
	v_ashrrev_i32_e32 v47, 31, v46
	v_ashrrev_i32_e32 v53, 31, v52
	v_ashrrev_i32_e32 v51, 31, v50
	v_lshlrev_b64 v[22:23], 14, v[22:23]
	v_lshl_add_u64 v[24:25], v[14:15], 0, v[24:25]
	v_lshlrev_b64 v[26:27], 14, v[26:27]
	v_lshlrev_b64 v[28:29], 14, v[28:29]
	v_lshlrev_b64 v[30:31], 14, v[30:31]
	v_lshlrev_b64 v[32:33], 14, v[32:33]
	v_lshlrev_b64 v[34:35], 14, v[34:35]
	v_lshlrev_b64 v[36:37], 14, v[36:37]
	v_lshlrev_b64 v[38:39], 14, v[38:39]
	v_lshlrev_b64 v[40:41], 14, v[40:41]
	v_lshlrev_b64 v[42:43], 14, v[42:43]
	v_lshlrev_b64 v[44:45], 14, v[44:45]
	v_lshlrev_b64 v[46:47], 14, v[46:47]
	v_lshlrev_b64 v[48:49], 14, v[48:49]
	v_lshlrev_b64 v[50:51], 14, v[50:51]
	v_lshlrev_b64 v[52:53], 14, v[52:53]
	v_lshl_add_u64 v[22:23], v[14:15], 0, v[22:23]
	v_lshl_add_u64 v[28:29], v[14:15], 0, v[28:29]
	v_lshl_add_u64 v[26:27], v[14:15], 0, v[26:27]
	v_lshl_add_u64 v[32:33], v[14:15], 0, v[32:33]
	v_lshl_add_u64 v[30:31], v[14:15], 0, v[30:31]
	v_lshl_add_u64 v[36:37], v[14:15], 0, v[36:37]
	v_lshl_add_u64 v[34:35], v[14:15], 0, v[34:35]
	v_lshl_add_u64 v[40:41], v[14:15], 0, v[40:41]
	v_lshl_add_u64 v[38:39], v[14:15], 0, v[38:39]
	v_lshl_add_u64 v[44:45], v[14:15], 0, v[44:45]
	v_lshl_add_u64 v[42:43], v[14:15], 0, v[42:43]
	v_lshl_add_u64 v[48:49], v[14:15], 0, v[48:49]
	v_lshl_add_u64 v[46:47], v[14:15], 0, v[46:47]
	v_lshl_add_u64 v[52:53], v[14:15], 0, v[52:53]
	v_lshl_add_u64 v[50:51], v[14:15], 0, v[50:51]
	global_load_dword v11, v[24:25], off
	global_load_dword v13, v[22:23], off
	global_load_dword v21, v[28:29], off
	global_load_dword v54, v[26:27], off
	global_load_dword v55, v[32:33], off
	global_load_dword v56, v[30:31], off
	global_load_dword v57, v[36:37], off
	global_load_dword v58, v[34:35], off
	global_load_dword v59, v[40:41], off
	global_load_dword v60, v[38:39], off
	global_load_dword v61, v[44:45], off
	global_load_dword v62, v[42:43], off
	global_load_dword v63, v[48:49], off
	global_load_dword v64, v[46:47], off
	global_load_dword v65, v[52:53], off
	global_load_dword v66, v[50:51], off
	v_or_b32_e32 v24, s38, v1
	v_or_b32_e32 v22, s39, v0
	s_add_i32 s36, s36, 16
	s_add_i32 s35, s35, 16
	s_add_i32 s37, s37, -16
	v_mad_u64_u32 v[22:23], s[38:39], v22, s53, v[4:5]
	v_mad_u64_u32 v[24:25], s[38:39], v24, s53, v[4:5]
	v_or_b32_e32 v23, s40, v1
	v_or_b32_e32 v25, s41, v0
	v_or_b32_e32 v32, s44, v1
	v_or_b32_e32 v30, s45, v0
	v_or_b32_e32 v36, s46, v1
	v_or_b32_e32 v34, s47, v0
	v_or_b32_e32 v40, s48, v1
	v_or_b32_e32 v38, s50, v0
	v_or_b32_e32 v44, s54, v1
	v_or_b32_e32 v42, s55, v0
	v_or_b32_e32 v48, s56, v1
	v_or_b32_e32 v46, s57, v0
	v_or_b32_e32 v52, s58, v1
	v_or_b32_e32 v50, s59, v0
	s_cmp_lg_u32 s37, 0
	v_mad_u64_u32 v[26:27], s[38:39], v25, s53, v[4:5]
	v_mad_u64_u32 v[28:29], s[38:39], v23, s53, v[4:5]
	v_mad_u64_u32 v[30:31], s[38:39], v30, s53, v[4:5]
	v_mad_u64_u32 v[32:33], s[38:39], v32, s53, v[4:5]
	v_mad_u64_u32 v[34:35], s[38:39], v34, s53, v[4:5]
	v_mad_u64_u32 v[36:37], s[38:39], v36, s53, v[4:5]
	v_mad_u64_u32 v[38:39], s[38:39], v38, s53, v[4:5]
	v_mad_u64_u32 v[40:41], s[38:39], v40, s53, v[4:5]
	v_mad_u64_u32 v[42:43], s[38:39], v42, s53, v[4:5]
	v_mad_u64_u32 v[44:45], s[38:39], v44, s53, v[4:5]
	v_mad_u64_u32 v[46:47], s[38:39], v46, s53, v[4:5]
	v_mad_u64_u32 v[48:49], s[38:39], v48, s53, v[4:5]
	v_mad_u64_u32 v[50:51], s[38:39], v50, s53, v[4:5]
	v_mad_u64_u32 v[52:53], s[38:39], v52, s53, v[4:5]
	s_waitcnt vmcnt(31)
; #define LAS __attribute__((address_space(3)))
; DI unsigned pk2(float lo, float hi) { f32x2 v = {lo, hi}; return __builtin_bit_cast(unsigned, __builtin_convertvector(v, bf16x2v)); }
; #define LDS_WAIT() asm volatile("s_waitcnt lgkmcnt(0)" ::: "memory")
; DI void p0_transpose_item(const float* W, int K, int N, bf16_t* WT, int up_map, LAS float* scr, int item, int lane) {
;     ...
;     for (int i = 0; i < 32; ++i) { const int kk = 2 * i + (lane >> 5); scr[kk * 33 + (lane & 31)] = W[(size_t)(k0 + kk) * N + n0 + (lane & 31)]; }
;     LDS_WAIT(); asm volatile("" ::: "memory");
;     const int c = lane & 7;
; #pragma unroll
;     for (int j = 0; j < 4; ++j) { const int n = (lane >> 3) + 8 * j; const LAS float* s = scr + (8 * c) * 33 + n;
;         u32x4 o; o.x = pk2(s[0 * 33], s[1 * 33]); o.y = pk2(s[2 * 33], s[3 * 33]); o.z = pk2(s[4 * 33], s[5 * 33]); o.w = pk2(s[6 * 33], s[7 * 33]);
;         *(u32x4*)(WT + (size_t)(rowbase + n) * K + k0 + 8 * c) = o; }
;     LDS_WAIT(); asm volatile("" ::: "memory");
; DI void p0_prologue(LAS unsigned char* lds, ArgsRef a) {
;     ...
;     for (int it = gw; it < 2 * 23040; it += NGW) {
;         const int l = it / 23040; int r = it - l * 23040;
;         if (r < 4096) { p0_transpose_item(a.in[I_WIN] + (size_t)l * 2048 * 4096, 2048, 4096, (bf16_t*)(ws + WS_WIN) + (size_t)l * 4096 * 2048, 0, scr, r, lane); continue; } r -= 4096;
;         if (r < 2048) { p0_transpose_item(a.in[I_WOUT] + (size_t)l * 2048 * 2048, 2048, 2048, (bf16_t*)(ws + WS_WOUT) + (size_t)l * 2048 * 2048, 0, scr, r, lane); continue; } r -= 2048;
;         if (r < 11264) { p0_transpose_item(a.in[I_WUP] + (size_t)l * 2048 * DFF2, 2048, DFF2, (bf16_t*)(ws + WS_WUP) + (size_t)l * DFF2 * 2048, 1, scr, r, lane); continue; } r -= 11264;
;         p0_transpose_item(a.in[I_WDOWN] + (size_t)l * DFF * 2048, DFF, 2048, (bf16_t*)(ws + WS_WDN) + (size_t)l * 2048 * DFF, 0, scr, r, lane);
;     }
	ds_write_b32 v100, v95
	s_waitcnt vmcnt(30)
	ds_write_b32 v102, v97
	s_waitcnt vmcnt(29)
	ds_write_b32 v104, v99
	s_waitcnt vmcnt(28)
	ds_write_b32 v106, v160
	s_waitcnt vmcnt(27)
	ds_write_b32 v108, v161
	s_waitcnt vmcnt(26)
	ds_write_b32 v110, v162
	s_waitcnt vmcnt(25)
	ds_write_b32 v112, v163
	s_waitcnt vmcnt(24)
	ds_write_b32 v114, v164
	s_waitcnt vmcnt(23)
	ds_write_b32 v116, v165
	s_waitcnt vmcnt(22)
	ds_write_b32 v118, v166
	s_waitcnt vmcnt(21)
	ds_write_b32 v120, v167
	s_waitcnt vmcnt(20)
	ds_write_b32 v122, v168
	s_waitcnt vmcnt(19)
	ds_write_b32 v124, v169
	s_waitcnt vmcnt(18)
	ds_write_b32 v126, v170
	s_waitcnt vmcnt(17)
	ds_write_b32 v156, v171
	s_waitcnt vmcnt(16)
	ds_write_b32 v158, v172
	s_waitcnt vmcnt(15)
	ds_write_b32 v22, v11
	s_waitcnt vmcnt(14)
	ds_write_b32 v24, v13
	s_waitcnt vmcnt(13)
	ds_write_b32 v26, v21
	s_waitcnt vmcnt(12)
	ds_write_b32 v28, v54
	s_waitcnt vmcnt(11)
	ds_write_b32 v30, v55
	s_waitcnt vmcnt(10)
	ds_write_b32 v32, v56
	s_waitcnt vmcnt(9)
	ds_write_b32 v34, v57
	s_waitcnt vmcnt(8)
	ds_write_b32 v36, v58
	s_waitcnt vmcnt(7)
	ds_write_b32 v38, v59
	s_waitcnt vmcnt(6)
	ds_write_b32 v40, v60
	s_waitcnt vmcnt(5)
	ds_write_b32 v42, v61
	s_waitcnt vmcnt(4)
	ds_write_b32 v44, v62
	s_waitcnt vmcnt(3)
	ds_write_b32 v46, v63
	s_waitcnt vmcnt(2)
	ds_write_b32 v48, v64
	s_waitcnt vmcnt(1)
	ds_write_b32 v50, v65
	s_waitcnt vmcnt(0)
	ds_write_b32 v52, v66
	s_waitcnt lgkmcnt(0)
	ds_read2_b32 v[22:23], v17 offset0:33 offset1:41
	ds_read2_b32 v[24:25], v17 offset1:8
	ds_read2_b32 v[26:27], v17 offset0:66 offset1:74
	ds_read2_b32 v[28:29], v17 offset0:99 offset1:107
	ds_read2_b32 v[30:31], v17 offset0:132 offset1:140
	ds_read2_b32 v[32:33], v17 offset0:165 offset1:173
	ds_read2_b32 v[34:35], v17 offset0:198 offset1:206
	ds_read2_b32 v[36:37], v17 offset0:231 offset1:239
	v_lshlrev_b64 v[8:9], 24, v[8:9]
	v_lshl_add_u64 v[8:9], s[12:13], 0, v[8:9]
	v_ashrrev_i32_e32 v13, 31, v12
	v_or_b32_e32 v38, v10, v7
	v_lshl_add_u64 v[8:9], v[12:13], 1, v[8:9]
	v_lshlrev_b32_e32 v184, 1, v6
	v_ashrrev_i32_e32 v39, 31, v38
	v_lshl_add_u64 v[8:9], v[8:9], 0, v[184:185]
	v_lshlrev_b64 v[38:39], 12, v[38:39]
	s_waitcnt lgkmcnt(6)
	v_cvt_pk_bf16_f32 v12, v24, v22
	s_waitcnt lgkmcnt(4)
	v_cvt_pk_bf16_f32 v13, v26, v28
	s_waitcnt lgkmcnt(2)
	v_cvt_pk_bf16_f32 v14, v30, v32
	s_waitcnt lgkmcnt(0)
	v_cvt_pk_bf16_f32 v15, v34, v36
	v_lshl_add_u64 v[38:39], v[8:9], 0, v[38:39]
	v_or_b32_e32 v22, v10, v18
	global_store_dwordx4 v[38:39], v[12:15], off
	s_nop 1
	v_cvt_pk_bf16_f32 v12, v25, v23
	v_ashrrev_i32_e32 v23, 31, v22
	v_cvt_pk_bf16_f32 v13, v27, v29
	v_cvt_pk_bf16_f32 v14, v31, v33
	v_cvt_pk_bf16_f32 v15, v35, v37
	v_lshlrev_b64 v[22:23], 12, v[22:23]
	ds_read2_b32 v[24:25], v17 offset0:49 offset1:57
	ds_read2_b32 v[26:27], v17 offset0:16 offset1:24
	ds_read2_b32 v[28:29], v17 offset0:82 offset1:90
	ds_read2_b32 v[30:31], v17 offset0:115 offset1:123
	ds_read2_b32 v[32:33], v17 offset0:148 offset1:156
	ds_read2_b32 v[34:35], v17 offset0:181 offset1:189
	ds_read2_b32 v[36:37], v17 offset0:214 offset1:222
	ds_read2_b32 v[38:39], v17 offset0:247 offset1:255
	v_lshl_add_u64 v[22:23], v[8:9], 0, v[22:23]
	global_store_dwordx4 v[22:23], v[12:15], off
	v_or_b32_e32 v22, v10, v19
	v_ashrrev_i32_e32 v23, 31, v22
	v_or_b32_e32 v10, v10, v20
	v_lshlrev_b64 v[22:23], 12, v[22:23]
	v_ashrrev_i32_e32 v11, 31, v10
	s_waitcnt lgkmcnt(6)
	v_cvt_pk_bf16_f32 v12, v26, v24
	s_waitcnt lgkmcnt(4)
	v_cvt_pk_bf16_f32 v13, v28, v30
	s_waitcnt lgkmcnt(2)
	v_cvt_pk_bf16_f32 v14, v32, v34
	s_waitcnt lgkmcnt(0)
	v_cvt_pk_bf16_f32 v15, v36, v38
	v_lshl_add_u64 v[22:23], v[8:9], 0, v[22:23]
	v_lshlrev_b64 v[10:11], 12, v[10:11]
	global_store_dwordx4 v[22:23], v[12:15], off
	v_lshl_add_u64 v[8:9], v[8:9], 0, v[10:11]
	s_nop 0
	v_cvt_pk_bf16_f32 v12, v27, v25
	v_cvt_pk_bf16_f32 v13, v29, v31
	v_cvt_pk_bf16_f32 v14, v33, v35
	v_cvt_pk_bf16_f32 v15, v37, v39
	global_store_dwordx4 v[8:9], v[12:15], off
	s_waitcnt lgkmcnt(0)
	s_branch .LBB0_797
